# adds: G1 tile head - wave 1 decodes the head-norm gain pointer once per tile instead of four times (all gained segments of a tile share it), shortening the straggler wave before the first K-tile barri
# speedup vs baseline: 1.0052x; 1.0037x over previous
; DI const float* gain_ptr(const Params& p, int l, int f0) {
;   if (f0 < 1536) return p.a_q_norm + (l * 3 + (f0 >> 9)) * 64;
;   if (f0 < 3072) return p.a_k_norm + (l * 3 + ((f0 - 1536) >> 9)) * 64;
;   if (f0 >= 5120 && f0 < 5632) return p.b_q_norm + l * 64;
;   if (f0 >= 5632 && f0 < 5760) return p.b_k_norm + l * 64;
;   return nullptr;
; }
; template <int CT>
; DI void phase_g1(int c, int l) {
;     ...
;       if (wid0 == 0) {
;         __builtin_amdgcn_global_load_lds((const unsigned*)(ssq + tbase + lane0 * 4), (unsigned*)(shm + EXT_SSQ), 16, 0, 0);
;       } else if (wid0 == 1) {
;         const int sg = lane0 >> 4;
;         const float* g0 = gain_ptr(p, l, fbase), *g1 = gain_ptr(p, l, fbase + 64), *g2 = gain_ptr(p, l, fbase + 128), *g3 = gain_ptr(p, l, fbase + 192);
;         const float* gp = sg == 0 ? g0 : sg == 1 ? g1 : sg == 2 ? g2 : g3;
;         if (!gp) gp = p.a_q_norm;
;         __builtin_amdgcn_global_load_lds((const unsigned*)(gp + (lane0 & 15) * 4), (unsigned*)(shm + EXT_GAIN), 16, 0, 0);
;       }
.LBB0_467:
.LBB0_491:
	s_mov_b32 m0, 0x25400
	v_mov_b32_e32 v4, s4
	v_mov_b32_e32 v5, s5
	v_mov_b32_e32 v0, s13
	v_cmp_eq_u64_e32 vcc, 0, v[4:5]
	s_nop 1
	v_cndmask_b32_e32 v5, v5, v0, vcc
	v_mov_b32_e32 v0, s12
	v_cndmask_b32_e32 v4, v4, v0, vcc
	v_lshlrev_b32_e32 v0, 4, v18
	v_and_b32_e32 v0, 0xf0, v0
	v_lshl_add_u64 v[4:5], v[4:5], 0, v[0:1]
	global_load_lds_dwordx4 v[4:5], off

; #define LOAD_PARAMS() KParams kq_ = (KParams)__builtin_amdgcn_kernarg_segment_ptr(); asm volatile("" : "+s"(kq_)); const Params p = *kq_
; template <int CT>
; __global__ void __launch_bounds__(NTHREADS) mega_kernel(Params p) {
;     ...
; #pragma unroll 1
;   for (int ph = 0; ph < nph; ++ph) {
;     run_phase<CT>(ph);
;     if (ph + 1 < nph) {
;       LOAD_PARAMS();
;       xcd_barrier((unsigned*)(p.ws + WS<CT>::bar), x, nloc, nx, k);
;       ++k;
;     }
;   }
; }
.LBB0_726:
	s_endpgm
	s_nop 0
	s_nop 0
	s_nop 0
	s_nop 0
	s_nop 0
	s_nop 0
	s_nop 0
	s_nop 0
	s_nop 0
	s_nop 0
	s_nop 0
	s_nop 0
	s_nop 0
	s_nop 0
	s_nop 0
	s_nop 0
	s_nop 0
	s_nop 0
	s_nop 0
	s_nop 0
	s_nop 0
	s_nop 0
	s_nop 0
	s_nop 0
	s_nop 0
	s_nop 0
	s_nop 0
	s_nop 0
	s_nop 0
	s_nop 0
	s_nop 0
	s_nop 0
	s_nop 0
	s_nop 0
	s_nop 0
	s_nop 0
	s_nop 0
	s_nop 0
	s_nop 0
	s_nop 0
	s_nop 0
	s_nop 0
	s_nop 0
	s_nop 0
	s_nop 0
	s_nop 0
	s_nop 0
	s_nop 0
	s_nop 0
	s_nop 0
	s_endpgm
